# v15 + the gate-column waves of the in-proj GEMM also take the coalesced epilogue (their f32 gate stores issued first, same values and addresses)
# baseline (speedup 1.0000x reference)
;     DI void operator()(const f32x4 (&acc)[2][2][4][2], const Unit& u, int wr, int wc, int fr, int fq) const {
;         const int row0 = u.pm * BM + wr * 64 + fr, col0 = u.pn * BM + wc * 32 + 8 * fq;
; #pragma unroll
;         for (int ai = 0; ai < 2; ++ai)
; #pragma unroll
;             for (int m = 0; m < 4; ++m) { const size_t row = (size_t)(row0 + ai * HALF + m * 16);
;     ...
;                     int gc = -1; if (col >= C_GC && col < C_GC + 32) gc = col - C_GC; else if (col >= C_ID && col < C_ID + 16) gc = 32 + col - C_ID;
;                     if (gc >= 0) { float* gp = GATE + row * 48 + gc; *(f32x4*)gp = v0; *(f32x4*)(gp + 4) = v1; } } }
.LBB0_158:
	s_lshl_b32 s74, s25, 8
	v_readlane_b32 s75, v253, 17
	s_or_b32 s74, s74, s75
	v_mbcnt_lo_u32_b32 v186, -1, 0
	v_mbcnt_hi_u32_b32 v186, -1, v186
	s_cmpk_eq_u32 s74, 0x700
	s_cbranch_scc1 .Lip_gc
	s_cmpk_eq_u32 s74, 0xb20
	s_cbranch_scc1 .Lip_id
	s_branch .Lip_main
.Lip_gc:
	v_lshrrev_b32_e32 v184, 4, v186
	v_lshlrev_b32_e32 v184, 5, v184
	s_branch .Lip_gate
.Lip_id:
	v_lshrrev_b32_e32 v184, 4, v186
	v_lshlrev_b32_e32 v184, 5, v184
	v_add_u32_e32 v184, 0x80, v184
	s_mov_b64 exec, 0xffffffff
.Lip_gate:
	v_readlane_b32 s75, v253, 14
	v_and_b32_e32 v185, 15, v186
	s_lshr_b32 s75, s75, 12
	s_lshl_b32 s75, s75, 6
	v_add_u32_e32 v185, s75, v185
	v_mov_b32_e32 v186, 0xc0
	v_mad_u32_u24 v185, v185, v186, v184
	s_mul_i32 s75, s26, 0xc000
	s_add_u32 s84, s28, s75
	s_addc_u32 s85, s29, 0
	global_store_dwordx4 v185, v[126:129], s[84:85]
	global_store_dwordx4 v185, v[122:125], s[84:85] offset:16
	s_add_u32 s84, s84, 0xc00
	s_addc_u32 s85, s85, 0
	global_store_dwordx4 v185, v[108:111], s[84:85]
	global_store_dwordx4 v185, v[104:107], s[84:85] offset:16
	s_add_u32 s84, s84, 0xc00
	s_addc_u32 s85, s85, 0
	global_store_dwordx4 v185, v[92:95], s[84:85]
	global_store_dwordx4 v185, v[88:91], s[84:85] offset:16
	s_add_u32 s84, s84, 0xc00
	s_addc_u32 s85, s85, 0
	global_store_dwordx4 v185, v[76:79], s[84:85]
	global_store_dwordx4 v185, v[72:75], s[84:85] offset:16
	s_add_u32 s84, s84, 0x3c00
	s_addc_u32 s85, s85, 0
	global_store_dwordx4 v185, v[60:63], s[84:85]
	global_store_dwordx4 v185, v[56:59], s[84:85] offset:16
	s_add_u32 s84, s84, 0xc00
	s_addc_u32 s85, s85, 0
	global_store_dwordx4 v185, v[44:47], s[84:85]
	global_store_dwordx4 v185, v[40:43], s[84:85] offset:16
	s_add_u32 s84, s84, 0xc00
	s_addc_u32 s85, s85, 0
	global_store_dwordx4 v185, v[28:31], s[84:85]
	global_store_dwordx4 v185, v[24:27], s[84:85] offset:16
	s_add_u32 s84, s84, 0xc00
	s_addc_u32 s85, s85, 0
	global_store_dwordx4 v185, v[12:15], s[84:85]
	global_store_dwordx4 v185, v[8:11], s[84:85] offset:16
	s_mov_b64 exec, -1
; DI unsigned pk2(float lo, float hi) { f32x2 v = {lo, hi}; bf2_t r = __builtin_convertvector(v, bf2_t); return __builtin_bit_cast(unsigned, r); }
;     DI void operator()(const f32x4 (&acc)[2][2][4][2], const Unit& u, int wr, int wc, int fr, int fq) const {
;         const int row0 = u.pm * BM + wr * 64 + fr, col0 = u.pn * BM + wc * 32 + 8 * fq;
; #pragma unroll
;         for (int ai = 0; ai < 2; ++ai)
; #pragma unroll
;             for (int m = 0; m < 4; ++m) { const size_t row = (size_t)(row0 + ai * HALF + m * 16);
; #pragma unroll
;                 for (int bj = 0; bj < 2; ++bj) { const int col = col0 + bj * HALF; const f32x4 v0 = acc[ai][bj][m][0], v1 = acc[ai][bj][m][1];
;                     u32x4 w; w.x = pk2(v0[0], v0[1]); w.y = pk2(v0[2], v0[3]); w.z = pk2(v1[0], v1[1]); w.w = pk2(v1[2], v1[3]);
;                     *(u32x4*)(Z + row * ZW + col) = w;
.Lip_main:
	v_mbcnt_lo_u32_b32 v156, -1, 0
	v_mbcnt_hi_u32_b32 v156, -1, v156
	v_readlane_b32 s74, v253, 14
	v_readlane_b32 s76, v253, 12
	v_readlane_b32 s77, v253, 13
	v_and_b32_e32 v157, 15, v156
	v_lshrrev_b32_e32 v158, 4, v156
	v_bfe_u32 v159, v156, 2, 2
	v_xor_b32_e32 v159, v159, v158
	v_lshlrev_b32_e32 v159, 4, v159
	v_lshl_or_b32 v157, v157, 6, v159
	v_and_b32_e32 v159, 3, v156
	v_xor_b32_e32 v158, v158, v159
	v_lshlrev_b32_e32 v158, 4, v158
	v_lshrrev_b32_e32 v156, 2, v156
	v_lshl_or_b32 v158, v156, 6, v158
	s_add_i32 s75, s74, 0xc000
	v_add_u32_e32 v157, s75, v157
	v_add_u32_e32 v158, s75, v158
	v_lshlrev_b32_e32 v159, 4, v159
	v_mov_b32_e32 v160, 0x1800
	v_mad_u32_u24 v159, v156, v160, v159
	s_lshr_b32 s74, s74, 10
	s_lshr_b32 s75, s74, 2
	s_and_b32 s74, s74, 3
	s_mul_i32 s75, s75, 0x60000
	s_lshl_b32 s74, s74, 6
	s_add_i32 s75, s75, s74
	v_add_u32_e32 v159, s75, v159
	s_mul_i32 s75, s26, 0x180000
	s_lshl_b32 s74, s25, 9
	s_add_u32 s75, s75, s74
	s_add_u32 s76, s76, s75
	s_addc_u32 s77, s77, 0
	v_cvt_pk_bf16_f32 v160, v126, v127
	v_cvt_pk_bf16_f32 v161, v128, v129
	v_cvt_pk_bf16_f32 v162, v122, v123
	v_cvt_pk_bf16_f32 v163, v124, v125
	ds_write_b128 v157, v[160:163]
	ds_read_b128 v[168:171], v158
	v_cvt_pk_bf16_f32 v164, v118, v119
	v_cvt_pk_bf16_f32 v165, v120, v121
	v_cvt_pk_bf16_f32 v166, v114, v115
	v_cvt_pk_bf16_f32 v167, v116, v117
	ds_write_b128 v157, v[164:167] offset:8192
	ds_read_b128 v[172:175], v158 offset:8192
	s_waitcnt lgkmcnt(2)
	global_store_dwordx4 v159, v[168:171], s[76:77]
	v_cvt_pk_bf16_f32 v160, v108, v109
	v_cvt_pk_bf16_f32 v161, v110, v111
	v_cvt_pk_bf16_f32 v162, v104, v105
	v_cvt_pk_bf16_f32 v163, v106, v107
	ds_write_b128 v157, v[160:163]
	ds_read_b128 v[176:179], v158
	s_waitcnt lgkmcnt(2)
	global_store_dwordx4 v159, v[172:175], s[76:77] offset:256
	v_cvt_pk_bf16_f32 v164, v100, v101
	v_cvt_pk_bf16_f32 v165, v102, v103
	v_cvt_pk_bf16_f32 v166, v96, v97
	v_cvt_pk_bf16_f32 v167, v98, v99
	ds_write_b128 v157, v[164:167] offset:8192
	ds_read_b128 v[180:183], v158 offset:8192
	s_waitcnt lgkmcnt(2)
	s_add_u32 s76, s76, 0x18000
	s_addc_u32 s77, s77, 0
	global_store_dwordx4 v159, v[176:179], s[76:77]
	v_cvt_pk_bf16_f32 v160, v92, v93
	v_cvt_pk_bf16_f32 v161, v94, v95
	v_cvt_pk_bf16_f32 v162, v88, v89
	v_cvt_pk_bf16_f32 v163, v90, v91
	ds_write_b128 v157, v[160:163]
	ds_read_b128 v[168:171], v158
	s_waitcnt lgkmcnt(2)
	global_store_dwordx4 v159, v[180:183], s[76:77] offset:256
	v_cvt_pk_bf16_f32 v164, v84, v85
	v_cvt_pk_bf16_f32 v165, v86, v87
	v_cvt_pk_bf16_f32 v166, v80, v81
	v_cvt_pk_bf16_f32 v167, v82, v83
	ds_write_b128 v157, v[164:167] offset:8192
	ds_read_b128 v[172:175], v158 offset:8192
	s_waitcnt lgkmcnt(2)
	s_add_u32 s76, s76, 0x18000
	s_addc_u32 s77, s77, 0
	global_store_dwordx4 v159, v[168:171], s[76:77]
	v_cvt_pk_bf16_f32 v160, v76, v77
	v_cvt_pk_bf16_f32 v161, v78, v79
	v_cvt_pk_bf16_f32 v162, v72, v73
	v_cvt_pk_bf16_f32 v163, v74, v75
	ds_write_b128 v157, v[160:163]
	ds_read_b128 v[176:179], v158
	s_waitcnt lgkmcnt(2)
	global_store_dwordx4 v159, v[172:175], s[76:77] offset:256
	v_cvt_pk_bf16_f32 v164, v68, v69
	v_cvt_pk_bf16_f32 v165, v70, v71
	v_cvt_pk_bf16_f32 v166, v64, v65
	v_cvt_pk_bf16_f32 v167, v66, v67
	ds_write_b128 v157, v[164:167] offset:8192
	ds_read_b128 v[180:183], v158 offset:8192
	s_waitcnt lgkmcnt(2)
	s_add_u32 s76, s76, 0x18000
	s_addc_u32 s77, s77, 0
	global_store_dwordx4 v159, v[176:179], s[76:77]
	v_cvt_pk_bf16_f32 v160, v60, v61
	v_cvt_pk_bf16_f32 v161, v62, v63
	v_cvt_pk_bf16_f32 v162, v56, v57
	v_cvt_pk_bf16_f32 v163, v58, v59
	ds_write_b128 v157, v[160:163]
	ds_read_b128 v[168:171], v158
	s_waitcnt lgkmcnt(2)
	global_store_dwordx4 v159, v[180:183], s[76:77] offset:256
	v_cvt_pk_bf16_f32 v164, v52, v53
	v_cvt_pk_bf16_f32 v165, v54, v55
	v_cvt_pk_bf16_f32 v166, v48, v49
	v_cvt_pk_bf16_f32 v167, v50, v51
	ds_write_b128 v157, v[164:167] offset:8192
	ds_read_b128 v[172:175], v158 offset:8192
	s_waitcnt lgkmcnt(2)
	s_add_u32 s76, s76, 0x78000
	s_addc_u32 s77, s77, 0
	global_store_dwordx4 v159, v[168:171], s[76:77]
	v_cvt_pk_bf16_f32 v160, v44, v45
	v_cvt_pk_bf16_f32 v161, v46, v47
	v_cvt_pk_bf16_f32 v162, v40, v41
	v_cvt_pk_bf16_f32 v163, v42, v43
	ds_write_b128 v157, v[160:163]
	ds_read_b128 v[176:179], v158
	s_waitcnt lgkmcnt(2)
	global_store_dwordx4 v159, v[172:175], s[76:77] offset:256
	v_cvt_pk_bf16_f32 v164, v36, v37
	v_cvt_pk_bf16_f32 v165, v38, v39
	v_cvt_pk_bf16_f32 v166, v32, v33
	v_cvt_pk_bf16_f32 v167, v34, v35
	ds_write_b128 v157, v[164:167] offset:8192
	ds_read_b128 v[180:183], v158 offset:8192
	s_waitcnt lgkmcnt(2)
	s_add_u32 s76, s76, 0x18000
	s_addc_u32 s77, s77, 0
	global_store_dwordx4 v159, v[176:179], s[76:77]
	v_cvt_pk_bf16_f32 v160, v28, v29
	v_cvt_pk_bf16_f32 v161, v30, v31
	v_cvt_pk_bf16_f32 v162, v24, v25
	v_cvt_pk_bf16_f32 v163, v26, v27
	ds_write_b128 v157, v[160:163]
	ds_read_b128 v[168:171], v158
	s_waitcnt lgkmcnt(2)
	global_store_dwordx4 v159, v[180:183], s[76:77] offset:256
	v_cvt_pk_bf16_f32 v164, v20, v21
	v_cvt_pk_bf16_f32 v165, v22, v23
	v_cvt_pk_bf16_f32 v166, v16, v17
	v_cvt_pk_bf16_f32 v167, v18, v19
	ds_write_b128 v157, v[164:167] offset:8192
	ds_read_b128 v[172:175], v158 offset:8192
	s_waitcnt lgkmcnt(2)
	s_add_u32 s76, s76, 0x18000
	s_addc_u32 s77, s77, 0
	global_store_dwordx4 v159, v[168:171], s[76:77]
	v_cvt_pk_bf16_f32 v160, v12, v13
	v_cvt_pk_bf16_f32 v161, v14, v15
	v_cvt_pk_bf16_f32 v162, v8, v9
	v_cvt_pk_bf16_f32 v163, v10, v11
	ds_write_b128 v157, v[160:163]
	ds_read_b128 v[176:179], v158
	s_waitcnt lgkmcnt(2)
	global_store_dwordx4 v159, v[172:175], s[76:77] offset:256
	v_cvt_pk_bf16_f32 v164, v4, v5
	v_cvt_pk_bf16_f32 v165, v6, v7
	v_cvt_pk_bf16_f32 v166, v0, v1
	v_cvt_pk_bf16_f32 v167, v2, v3
	ds_write_b128 v157, v[164:167] offset:8192
	ds_read_b128 v[180:183], v158 offset:8192
	s_waitcnt lgkmcnt(2)
	s_add_u32 s76, s76, 0x18000
	s_addc_u32 s77, s77, 0
	global_store_dwordx4 v159, v[176:179], s[76:77]
	s_waitcnt lgkmcnt(0)
	global_store_dwordx4 v159, v[180:183], s[76:77] offset:256
	s_movk_i32 s36, 0x44
	s_andn2_b64 vcc, exec, s[0:1]
	s_mov_b64 s[0:1], -1
	s_cbranch_vccnz .LBB0_151
	s_branch .Lepi_ip_after
	s_nop 0
